# dma+cvt2 + sc1 (write-through) policy on P1 projection epilogue stores
# baseline (speedup 1.0000x reference)
.LBB0_127:
	s_add_u32 s0, s10, s30
	s_addc_u32 s1, s11, s31
	s_cmp_eq_u32 s28, 0
	s_cselect_b64 s[30:31], -1, 0
	s_lshl_b32 s19, s48, 8
	v_readlane_b32 s21, v254, 61
	s_add_i32 s19, s19, s21
	v_and_or_b32 v169, v122, 15, s19
	s_lshl_b32 s19, s47, 8
	s_or_b32 s19, s19, s81
	v_ashrrev_i32_e32 v122, 1, v122
	s_cmp_gt_i32 s47, 39
	v_and_b32_e32 v122, -8, v122
	s_cselect_b64 s[34:35], -1, 0
	v_add_u32_e32 v156, s19, v122
	s_and_b64 s[48:49], s[30:31], s[34:35]
	s_mov_b64 s[34:35], -1
	s_and_b64 vcc, exec, s[48:49]
	v_ashrrev_i32_e32 v157, 31, v156
	v_or_b32_e32 v168, 16, v169
	v_or_b32_e32 v167, 32, v169
	v_or_b32_e32 v166, 48, v169
	v_add_u32_e32 v165, 0x80, v169
	v_add_u32_e32 v164, 0x90, v169
	v_add_u32_e32 v163, 0xa0, v169
	v_add_u32_e32 v162, 0xb0, v169
	s_cbranch_vccnz .LBB0_129
	s_cmp_eq_u32 s28, 1
	s_cselect_b32 s19, s84, 0x400
	s_and_b64 s[28:29], s[30:31], exec
	s_cselect_b32 s19, 0x4800, s19
	v_lshl_add_u64 v[126:127], v[156:157], 1, s[0:1]
	v_mad_i64_i32 v[122:123], s[28:29], s19, v169, 0
	v_lshl_add_u64 v[128:129], v[122:123], 1, v[126:127]
	v_cvt_pk_bf16_f32 v122, v142, v143
	v_cvt_pk_bf16_f32 v123, v144, v145
	v_cvt_pk_bf16_f32 v124, v138, v139
	v_cvt_pk_bf16_f32 v125, v140, v141
	global_store_dwordx4 v[128:129], v[122:125], off sc1
	s_mov_b64 s[34:35], 0
	s_nop 0
	v_cvt_pk_bf16_f32 v122, v118, v119
	v_cvt_pk_bf16_f32 v123, v120, v121
	v_cvt_pk_bf16_f32 v124, v114, v115
	v_cvt_pk_bf16_f32 v125, v116, v117
	global_store_dwordx4 v[128:129], v[122:125], off offset:256 sc1
	s_nop 1
	v_mad_i64_i32 v[122:123], s[28:29], s19, v168, 0
	v_lshl_add_u64 v[128:129], v[122:123], 1, v[126:127]
	v_cvt_pk_bf16_f32 v122, v110, v111
	v_cvt_pk_bf16_f32 v123, v112, v113
	v_cvt_pk_bf16_f32 v124, v106, v107
	v_cvt_pk_bf16_f32 v125, v108, v109
	global_store_dwordx4 v[128:129], v[122:125], off sc1
	s_nop 1
	v_cvt_pk_bf16_f32 v122, v102, v103
	v_cvt_pk_bf16_f32 v123, v104, v105
	v_cvt_pk_bf16_f32 v124, v98, v99
	v_cvt_pk_bf16_f32 v125, v100, v101
	global_store_dwordx4 v[128:129], v[122:125], off offset:256 sc1
	s_nop 1
	v_mad_i64_i32 v[122:123], s[28:29], s19, v167, 0
	v_lshl_add_u64 v[128:129], v[122:123], 1, v[126:127]
	v_cvt_pk_bf16_f32 v122, v94, v95
	v_cvt_pk_bf16_f32 v123, v96, v97
	v_cvt_pk_bf16_f32 v124, v90, v91
	v_cvt_pk_bf16_f32 v125, v92, v93
	global_store_dwordx4 v[128:129], v[122:125], off sc1
	s_nop 1
	v_cvt_pk_bf16_f32 v122, v86, v87
	v_cvt_pk_bf16_f32 v123, v88, v89
	v_cvt_pk_bf16_f32 v124, v82, v83
	v_cvt_pk_bf16_f32 v125, v84, v85
	global_store_dwordx4 v[128:129], v[122:125], off offset:256 sc1
	s_nop 1
	v_mad_i64_i32 v[122:123], s[28:29], s19, v166, 0
	v_lshl_add_u64 v[128:129], v[122:123], 1, v[126:127]
	v_cvt_pk_bf16_f32 v122, v78, v79
	v_cvt_pk_bf16_f32 v123, v80, v81
	v_cvt_pk_bf16_f32 v124, v74, v75
	v_cvt_pk_bf16_f32 v125, v76, v77
	global_store_dwordx4 v[128:129], v[122:125], off sc1
	s_nop 1
	v_cvt_pk_bf16_f32 v122, v70, v71
	v_cvt_pk_bf16_f32 v123, v72, v73
	v_cvt_pk_bf16_f32 v124, v66, v67
	v_cvt_pk_bf16_f32 v125, v68, v69
	global_store_dwordx4 v[128:129], v[122:125], off offset:256 sc1
	s_nop 1
	v_mad_i64_i32 v[122:123], s[28:29], s19, v165, 0
	v_lshl_add_u64 v[128:129], v[122:123], 1, v[126:127]
	v_cvt_pk_bf16_f32 v122, v62, v63
	v_cvt_pk_bf16_f32 v123, v64, v65
	v_cvt_pk_bf16_f32 v124, v58, v59
	v_cvt_pk_bf16_f32 v125, v60, v61
	global_store_dwordx4 v[128:129], v[122:125], off sc1
	s_nop 1
	v_cvt_pk_bf16_f32 v122, v54, v55
	v_cvt_pk_bf16_f32 v123, v56, v57
	v_cvt_pk_bf16_f32 v124, v50, v51
	v_cvt_pk_bf16_f32 v125, v52, v53
	global_store_dwordx4 v[128:129], v[122:125], off offset:256 sc1
	s_nop 1
	v_mad_i64_i32 v[122:123], s[28:29], s19, v164, 0
	v_lshl_add_u64 v[128:129], v[122:123], 1, v[126:127]
	v_cvt_pk_bf16_f32 v122, v46, v47
	v_cvt_pk_bf16_f32 v123, v48, v49
	v_cvt_pk_bf16_f32 v124, v42, v43
	v_cvt_pk_bf16_f32 v125, v44, v45
	global_store_dwordx4 v[128:129], v[122:125], off sc1
	s_nop 1
	v_cvt_pk_bf16_f32 v122, v38, v39
	v_cvt_pk_bf16_f32 v123, v40, v41
	v_cvt_pk_bf16_f32 v124, v34, v35
	v_cvt_pk_bf16_f32 v125, v36, v37
	global_store_dwordx4 v[128:129], v[122:125], off offset:256 sc1
	s_nop 1
	v_mad_i64_i32 v[122:123], s[28:29], s19, v163, 0
	v_lshl_add_u64 v[128:129], v[122:123], 1, v[126:127]
	v_cvt_pk_bf16_f32 v122, v30, v31
	v_cvt_pk_bf16_f32 v123, v32, v33
	v_cvt_pk_bf16_f32 v124, v26, v27
	v_cvt_pk_bf16_f32 v125, v28, v29
	global_store_dwordx4 v[128:129], v[122:125], off sc1
	s_nop 1
	v_cvt_pk_bf16_f32 v122, v22, v23
	v_cvt_pk_bf16_f32 v123, v24, v25
	v_cvt_pk_bf16_f32 v124, v18, v19
	v_cvt_pk_bf16_f32 v125, v20, v21
	global_store_dwordx4 v[128:129], v[122:125], off offset:256 sc1
	s_nop 1
	v_mad_i64_i32 v[122:123], s[28:29], s19, v162, 0
	v_lshl_add_u64 v[158:159], v[122:123], 1, v[126:127]
	v_cvt_pk_bf16_f32 v122, v14, v15
	v_cvt_pk_bf16_f32 v123, v16, v17
	v_cvt_pk_bf16_f32 v124, v10, v11
	v_cvt_pk_bf16_f32 v125, v12, v13
	global_store_dwordx4 v[158:159], v[122:125], off sc1
	s_nop 1
	v_cvt_pk_bf16_f32 v122, v6, v7
	v_cvt_pk_bf16_f32 v123, v8, v9
	v_cvt_pk_bf16_f32 v124, v2, v3
.LBB0_129:
	s_andn2_b64 vcc, exec, s[34:35]
	s_cbranch_vccnz .LBB0_131
	s_mov_b32 s28, 0xffff6000
	v_lshl_add_u64 v[122:123], v[156:157], 2, s[14:15]
	s_mov_b32 s29, -1
	v_lshl_add_u64 v[124:125], v[122:123], 0, s[28:29]
	v_add_co_u32_e32 v126, vcc, 0xffff6000, v122
	s_mov_b32 s28, 0xffff6200
	s_nop 0
	v_addc_co_u32_e32 v127, vcc, -1, v123, vcc
	s_mov_b32 s29, -1
	s_mov_b32 s19, 0xffff7000
	global_load_dwordx4 v[130:133], v[126:127], off
	global_load_dwordx4 v[134:137], v[124:125], off offset:16
	v_lshl_add_u64 v[126:127], v[122:123], 0, s[28:29]
	v_add_co_u32_e32 v122, vcc, s19, v122
	v_lshl_add_u64 v[156:157], v[156:157], 1, s[0:1]
	s_nop 0
	v_addc_co_u32_e32 v123, vcc, -1, v123, vcc
	global_load_dwordx4 v[122:125], v[122:123], off offset:-3584
	s_nop 0
	global_load_dwordx4 v[126:129], v[126:127], off offset:16
	v_mad_i64_i32 v[158:159], s[0:1], v169, s87, v[156:157]
	s_waitcnt vmcnt(0)
	v_add_f32_e32 v143, v143, v131
	v_add_f32_e32 v138, v138, v134
	v_add_f32_e32 v139, v139, v135
	v_add_f32_e32 v144, v144, v132
	v_add_f32_e32 v140, v140, v136
	v_add_f32_e32 v145, v145, v133
	v_max_f32_e32 v138, 0xc1f00000, v138
	v_add_f32_e32 v119, v119, v123
	v_add_f32_e32 v114, v114, v126
	v_max_f32_e32 v143, 0xc1f00000, v143
	v_max_f32_e32 v139, 0xc1f00000, v139
	v_max_f32_e32 v144, 0xc1f00000, v144
	v_max_f32_e32 v140, 0xc1f00000, v140
	v_max_f32_e32 v145, 0xc1f00000, v145
	v_max_f32_e32 v114, 0xc1f00000, v114
	v_max_f32_e32 v119, 0xc1f00000, v119
	v_mul_f32_e32 v138, 0xbfb8aa3b, v138
	v_mul_f32_e32 v143, 0xbfb8aa3b, v143
	v_mul_f32_e32 v139, 0xbfb8aa3b, v139
	v_mul_f32_e32 v144, 0xbfb8aa3b, v144
	v_mul_f32_e32 v140, 0xbfb8aa3b, v140
	v_mul_f32_e32 v145, 0xbfb8aa3b, v145
	v_mul_f32_e32 v114, 0xbfb8aa3b, v114
	v_mul_f32_e32 v119, 0xbfb8aa3b, v119
	v_exp_f32_e32 v138, v138
	v_exp_f32_e32 v143, v143
	v_exp_f32_e32 v139, v139
	v_exp_f32_e32 v144, v144
	v_exp_f32_e32 v140, v140
	v_exp_f32_e32 v145, v145
	v_exp_f32_e32 v114, v114
	v_exp_f32_e32 v119, v119
	v_add_f32_e32 v115, v115, v127
	v_add_f32_e32 v120, v120, v124
	v_max_f32_e32 v115, 0xc1f00000, v115
	v_add_f32_e32 v138, 1.0, v138
	v_add_f32_e32 v143, 1.0, v143
	v_add_f32_e32 v139, 1.0, v139
	v_add_f32_e32 v144, 1.0, v144
	v_add_f32_e32 v140, 1.0, v140
	v_add_f32_e32 v145, 1.0, v145
	v_add_f32_e32 v114, 1.0, v114
	v_add_f32_e32 v119, 1.0, v119
	v_mul_f32_e32 v115, 0xbfb8aa3b, v115
	v_rcp_f32_e32 v169, v138
	v_rcp_f32_e32 v138, v143
	v_rcp_f32_e32 v143, v139
	v_rcp_f32_e32 v139, v144
	v_rcp_f32_e32 v144, v140
	v_rcp_f32_e32 v140, v145
	v_rcp_f32_e32 v145, v114
	v_rcp_f32_e32 v114, v119
	v_max_f32_e32 v119, 0xc1f00000, v120
	v_exp_f32_e32 v115, v115
	v_mul_f32_e32 v119, 0xbfb8aa3b, v119
	v_exp_f32_e32 v119, v119
	v_add_f32_e32 v116, v116, v128
	v_add_f32_e32 v115, 1.0, v115
	v_add_f32_e32 v118, v118, v122
	v_max_f32_e32 v116, 0xc1f00000, v116
	v_rcp_f32_e32 v120, v115
	v_add_f32_e32 v115, 1.0, v119
	v_add_f32_e32 v119, v121, v125
	v_add_f32_e32 v117, v117, v129
	v_max_f32_e32 v118, 0xc1f00000, v118
	v_mul_f32_e32 v116, 0xbfb8aa3b, v116
	v_max_f32_e32 v119, 0xc1f00000, v119
	v_max_f32_e32 v117, 0xc1f00000, v117
	v_mul_f32_e32 v118, 0xbfb8aa3b, v118
	v_exp_f32_e32 v116, v116
	v_mul_f32_e32 v119, 0xbfb8aa3b, v119
	v_mul_f32_e32 v117, 0xbfb8aa3b, v117
	v_exp_f32_e32 v118, v118
	v_exp_f32_e32 v119, v119
	v_exp_f32_e32 v117, v117
	v_add_f32_e32 v106, v106, v134
	v_add_f32_e32 v116, 1.0, v116
	v_max_f32_e32 v106, 0xc1f00000, v106
	v_add_f32_e32 v111, v111, v131
	v_add_f32_e32 v118, 1.0, v118
	v_rcp_f32_e32 v121, v116
	v_add_f32_e32 v116, 1.0, v119
	v_add_f32_e32 v117, 1.0, v117
	v_mul_f32_e32 v106, 0xbfb8aa3b, v106
	v_max_f32_e32 v111, 0xc1f00000, v111
	v_rcp_f32_e32 v118, v118
	v_rcp_f32_e32 v115, v115
	v_rcp_f32_e32 v116, v116
	v_rcp_f32_e32 v117, v117
	v_exp_f32_e32 v106, v106
	v_mul_f32_e32 v111, 0xbfb8aa3b, v111
	v_exp_f32_e32 v111, v111
	v_cvt_pk_bf16_f32 v114, v118, v114
	v_cvt_pk_bf16_f32 v115, v115, v116
	v_cvt_pk_bf16_f32 v116, v145, v120
	v_cvt_pk_bf16_f32 v117, v121, v117
	v_add_f32_e32 v106, 1.0, v106
	v_add_f32_e32 v107, v107, v135
	global_store_dwordx4 v[158:159], v[114:117], off offset:256 sc1
	v_max_f32_e32 v107, 0xc1f00000, v107
	v_mul_f32_e32 v107, 0xbfb8aa3b, v107
	v_rcp_f32_e32 v116, v106
	v_add_f32_e32 v106, 1.0, v111
	v_add_f32_e32 v111, v112, v132
	v_max_f32_e32 v111, 0xc1f00000, v111
	v_exp_f32_e32 v107, v107
	v_mul_f32_e32 v111, 0xbfb8aa3b, v111
	v_exp_f32_e32 v111, v111
	v_add_f32_e32 v108, v108, v136
	v_add_f32_e32 v107, 1.0, v107
	v_add_f32_e32 v110, v110, v130
	v_max_f32_e32 v108, 0xc1f00000, v108
	v_rcp_f32_e32 v112, v107
	v_add_f32_e32 v107, 1.0, v111
	v_add_f32_e32 v111, v113, v133
	v_add_f32_e32 v109, v109, v137
	v_max_f32_e32 v110, 0xc1f00000, v110
	v_mul_f32_e32 v108, 0xbfb8aa3b, v108
	v_max_f32_e32 v111, 0xc1f00000, v111
	v_max_f32_e32 v109, 0xc1f00000, v109
	v_mul_f32_e32 v110, 0xbfb8aa3b, v110
	v_exp_f32_e32 v108, v108
	v_mul_f32_e32 v111, 0xbfb8aa3b, v111
	v_mul_f32_e32 v109, 0xbfb8aa3b, v109
	v_exp_f32_e32 v110, v110
	v_exp_f32_e32 v111, v111
	v_exp_f32_e32 v109, v109
	v_add_f32_e32 v98, v98, v126
	v_add_f32_e32 v108, 1.0, v108
	v_max_f32_e32 v98, 0xc1f00000, v98
	v_add_f32_e32 v103, v103, v123
	v_add_f32_e32 v110, 1.0, v110
	v_rcp_f32_e32 v113, v108
	v_add_f32_e32 v108, 1.0, v111
	v_add_f32_e32 v109, 1.0, v109
	v_mul_f32_e32 v98, 0xbfb8aa3b, v98
	v_max_f32_e32 v103, 0xc1f00000, v103
	v_rcp_f32_e32 v110, v110
	v_rcp_f32_e32 v106, v106
	v_rcp_f32_e32 v107, v107
	v_rcp_f32_e32 v108, v108
	v_rcp_f32_e32 v109, v109
	v_exp_f32_e32 v98, v98
	v_mul_f32_e32 v103, 0xbfb8aa3b, v103
	v_exp_f32_e32 v103, v103
	v_mad_i64_i32 v[114:115], s[0:1], v168, s87, v[156:157]
	v_cvt_pk_bf16_f32 v106, v110, v106
	v_cvt_pk_bf16_f32 v107, v107, v108
	v_cvt_pk_bf16_f32 v108, v116, v112
	v_cvt_pk_bf16_f32 v109, v113, v109
	v_add_f32_e32 v98, 1.0, v98
	v_add_f32_e32 v99, v99, v127
	global_store_dwordx4 v[114:115], v[106:109], off sc1
	v_max_f32_e32 v99, 0xc1f00000, v99
	v_mul_f32_e32 v99, 0xbfb8aa3b, v99
	v_rcp_f32_e32 v106, v98
	v_add_f32_e32 v98, 1.0, v103
	v_add_f32_e32 v103, v104, v124
	v_max_f32_e32 v103, 0xc1f00000, v103
	v_exp_f32_e32 v99, v99
	v_mul_f32_e32 v103, 0xbfb8aa3b, v103
	v_exp_f32_e32 v103, v103
	v_add_f32_e32 v100, v100, v128
	v_add_f32_e32 v99, 1.0, v99
	v_add_f32_e32 v102, v102, v122
	v_max_f32_e32 v100, 0xc1f00000, v100
	v_rcp_f32_e32 v104, v99
	v_add_f32_e32 v99, 1.0, v103
	v_add_f32_e32 v103, v105, v125
	v_add_f32_e32 v101, v101, v129
	v_max_f32_e32 v102, 0xc1f00000, v102
	v_mul_f32_e32 v100, 0xbfb8aa3b, v100
	v_max_f32_e32 v103, 0xc1f00000, v103
	v_max_f32_e32 v101, 0xc1f00000, v101
	v_mul_f32_e32 v102, 0xbfb8aa3b, v102
	v_exp_f32_e32 v100, v100
	v_mul_f32_e32 v103, 0xbfb8aa3b, v103
	v_mul_f32_e32 v101, 0xbfb8aa3b, v101
	v_exp_f32_e32 v102, v102
	v_exp_f32_e32 v103, v103
	v_exp_f32_e32 v101, v101
	v_add_f32_e32 v90, v90, v134
	v_add_f32_e32 v100, 1.0, v100
	v_max_f32_e32 v90, 0xc1f00000, v90
	v_add_f32_e32 v95, v95, v131
	v_add_f32_e32 v102, 1.0, v102
	v_rcp_f32_e32 v105, v100
	v_add_f32_e32 v100, 1.0, v103
	v_add_f32_e32 v101, 1.0, v101
	v_mul_f32_e32 v90, 0xbfb8aa3b, v90
	v_max_f32_e32 v95, 0xc1f00000, v95
	v_rcp_f32_e32 v102, v102
	v_rcp_f32_e32 v98, v98
	v_rcp_f32_e32 v99, v99
	v_rcp_f32_e32 v100, v100
	v_rcp_f32_e32 v101, v101
	v_exp_f32_e32 v90, v90
	v_mul_f32_e32 v95, 0xbfb8aa3b, v95
	v_exp_f32_e32 v95, v95
	v_cvt_pk_bf16_f32 v98, v102, v98
	v_cvt_pk_bf16_f32 v99, v99, v100
	v_cvt_pk_bf16_f32 v100, v106, v104
	v_cvt_pk_bf16_f32 v101, v105, v101
	v_add_f32_e32 v90, 1.0, v90
	v_add_f32_e32 v91, v91, v135
	global_store_dwordx4 v[114:115], v[98:101], off offset:256 sc1
	v_max_f32_e32 v91, 0xc1f00000, v91
	v_mul_f32_e32 v91, 0xbfb8aa3b, v91
	v_rcp_f32_e32 v100, v90
	v_add_f32_e32 v90, 1.0, v95
	v_add_f32_e32 v95, v96, v132
	v_max_f32_e32 v95, 0xc1f00000, v95
	v_exp_f32_e32 v91, v91
	v_mul_f32_e32 v95, 0xbfb8aa3b, v95
	v_exp_f32_e32 v95, v95
	v_add_f32_e32 v92, v92, v136
	v_add_f32_e32 v91, 1.0, v91
	v_add_f32_e32 v94, v94, v130
	v_max_f32_e32 v92, 0xc1f00000, v92
	v_rcp_f32_e32 v96, v91
	v_add_f32_e32 v91, 1.0, v95
	v_add_f32_e32 v95, v97, v133
	v_add_f32_e32 v93, v93, v137
	v_max_f32_e32 v94, 0xc1f00000, v94
	v_mul_f32_e32 v92, 0xbfb8aa3b, v92
	v_max_f32_e32 v95, 0xc1f00000, v95
	v_max_f32_e32 v93, 0xc1f00000, v93
	v_mul_f32_e32 v94, 0xbfb8aa3b, v94
	v_exp_f32_e32 v92, v92
	v_mul_f32_e32 v95, 0xbfb8aa3b, v95
	v_mul_f32_e32 v93, 0xbfb8aa3b, v93
	v_exp_f32_e32 v94, v94
	v_exp_f32_e32 v95, v95
	v_exp_f32_e32 v93, v93
	v_add_f32_e32 v82, v82, v126
	v_add_f32_e32 v92, 1.0, v92
	v_max_f32_e32 v82, 0xc1f00000, v82
	v_add_f32_e32 v87, v87, v123
	v_add_f32_e32 v94, 1.0, v94
	v_rcp_f32_e32 v97, v92
	v_add_f32_e32 v92, 1.0, v95
	v_add_f32_e32 v93, 1.0, v93
	v_mul_f32_e32 v82, 0xbfb8aa3b, v82
	v_max_f32_e32 v87, 0xc1f00000, v87
	v_rcp_f32_e32 v94, v94
	v_rcp_f32_e32 v90, v90
	v_rcp_f32_e32 v91, v91
	v_rcp_f32_e32 v92, v92
	v_rcp_f32_e32 v93, v93
	v_exp_f32_e32 v82, v82
	v_mul_f32_e32 v87, 0xbfb8aa3b, v87
	v_exp_f32_e32 v87, v87
	v_mad_i64_i32 v[98:99], s[0:1], v167, s87, v[156:157]
	v_cvt_pk_bf16_f32 v90, v94, v90
	v_cvt_pk_bf16_f32 v91, v91, v92
	v_cvt_pk_bf16_f32 v92, v100, v96
	v_cvt_pk_bf16_f32 v93, v97, v93
	v_add_f32_e32 v82, 1.0, v82
	v_add_f32_e32 v83, v83, v127
	global_store_dwordx4 v[98:99], v[90:93], off sc1
	v_max_f32_e32 v83, 0xc1f00000, v83
	v_mul_f32_e32 v83, 0xbfb8aa3b, v83
	v_rcp_f32_e32 v90, v82
	v_add_f32_e32 v82, 1.0, v87
	v_add_f32_e32 v87, v88, v124
	v_max_f32_e32 v87, 0xc1f00000, v87
	v_exp_f32_e32 v83, v83
	v_mul_f32_e32 v87, 0xbfb8aa3b, v87
	v_exp_f32_e32 v87, v87
	v_add_f32_e32 v84, v84, v128
	v_add_f32_e32 v83, 1.0, v83
	v_add_f32_e32 v86, v86, v122
	v_max_f32_e32 v84, 0xc1f00000, v84
	v_rcp_f32_e32 v88, v83
	v_add_f32_e32 v83, 1.0, v87
	v_add_f32_e32 v87, v89, v125
	v_add_f32_e32 v85, v85, v129
	v_max_f32_e32 v86, 0xc1f00000, v86
	v_mul_f32_e32 v84, 0xbfb8aa3b, v84
	v_max_f32_e32 v87, 0xc1f00000, v87
	v_max_f32_e32 v85, 0xc1f00000, v85
	v_mul_f32_e32 v86, 0xbfb8aa3b, v86
	v_exp_f32_e32 v84, v84
	v_mul_f32_e32 v87, 0xbfb8aa3b, v87
	v_mul_f32_e32 v85, 0xbfb8aa3b, v85
	v_exp_f32_e32 v86, v86
	v_exp_f32_e32 v87, v87
	v_exp_f32_e32 v85, v85
	v_add_f32_e32 v74, v74, v134
	v_add_f32_e32 v84, 1.0, v84
	v_max_f32_e32 v74, 0xc1f00000, v74
	v_add_f32_e32 v79, v79, v131
	v_add_f32_e32 v86, 1.0, v86
	v_rcp_f32_e32 v89, v84
	v_add_f32_e32 v84, 1.0, v87
	v_add_f32_e32 v85, 1.0, v85
	v_mul_f32_e32 v74, 0xbfb8aa3b, v74
	v_max_f32_e32 v79, 0xc1f00000, v79
	v_rcp_f32_e32 v86, v86
	v_rcp_f32_e32 v82, v82
	v_rcp_f32_e32 v83, v83
	v_rcp_f32_e32 v84, v84
	v_rcp_f32_e32 v85, v85
	v_exp_f32_e32 v74, v74
	v_mul_f32_e32 v79, 0xbfb8aa3b, v79
	v_exp_f32_e32 v79, v79
	v_cvt_pk_bf16_f32 v82, v86, v82
	v_cvt_pk_bf16_f32 v83, v83, v84
	v_cvt_pk_bf16_f32 v84, v90, v88
	v_cvt_pk_bf16_f32 v85, v89, v85
	v_add_f32_e32 v74, 1.0, v74
	v_add_f32_e32 v75, v75, v135
	global_store_dwordx4 v[98:99], v[82:85], off offset:256 sc1
	v_max_f32_e32 v75, 0xc1f00000, v75
	v_mul_f32_e32 v75, 0xbfb8aa3b, v75
	v_rcp_f32_e32 v84, v74
	v_add_f32_e32 v74, 1.0, v79
	v_add_f32_e32 v79, v80, v132
	v_max_f32_e32 v79, 0xc1f00000, v79
	v_exp_f32_e32 v75, v75
	v_mul_f32_e32 v79, 0xbfb8aa3b, v79
	v_exp_f32_e32 v79, v79
	v_add_f32_e32 v76, v76, v136
	v_add_f32_e32 v75, 1.0, v75
	v_add_f32_e32 v78, v78, v130
	v_max_f32_e32 v76, 0xc1f00000, v76
	v_rcp_f32_e32 v80, v75
	v_add_f32_e32 v75, 1.0, v79
	v_add_f32_e32 v79, v81, v133
	v_add_f32_e32 v77, v77, v137
	v_max_f32_e32 v78, 0xc1f00000, v78
	v_mul_f32_e32 v76, 0xbfb8aa3b, v76
	v_max_f32_e32 v79, 0xc1f00000, v79
	v_max_f32_e32 v77, 0xc1f00000, v77
	v_mul_f32_e32 v78, 0xbfb8aa3b, v78
	v_exp_f32_e32 v76, v76
	v_mul_f32_e32 v79, 0xbfb8aa3b, v79
	v_mul_f32_e32 v77, 0xbfb8aa3b, v77
	v_exp_f32_e32 v78, v78
	v_exp_f32_e32 v79, v79
	v_exp_f32_e32 v77, v77
	v_add_f32_e32 v66, v66, v126
	v_add_f32_e32 v76, 1.0, v76
	v_max_f32_e32 v66, 0xc1f00000, v66
	v_add_f32_e32 v71, v71, v123
	v_add_f32_e32 v78, 1.0, v78
	v_rcp_f32_e32 v81, v76
	v_add_f32_e32 v76, 1.0, v79
	v_add_f32_e32 v77, 1.0, v77
	v_mul_f32_e32 v66, 0xbfb8aa3b, v66
	v_max_f32_e32 v71, 0xc1f00000, v71
	v_rcp_f32_e32 v78, v78
	v_rcp_f32_e32 v74, v74
	v_rcp_f32_e32 v75, v75
	v_rcp_f32_e32 v76, v76
	v_rcp_f32_e32 v77, v77
	v_exp_f32_e32 v66, v66
	v_mul_f32_e32 v71, 0xbfb8aa3b, v71
	v_exp_f32_e32 v71, v71
	v_mad_i64_i32 v[82:83], s[0:1], v166, s87, v[156:157]
	v_cvt_pk_bf16_f32 v74, v78, v74
	v_cvt_pk_bf16_f32 v75, v75, v76
	v_cvt_pk_bf16_f32 v76, v84, v80
	v_cvt_pk_bf16_f32 v77, v81, v77
	v_add_f32_e32 v66, 1.0, v66
	v_add_f32_e32 v67, v67, v127
	global_store_dwordx4 v[82:83], v[74:77], off sc1
	v_max_f32_e32 v67, 0xc1f00000, v67
	v_mul_f32_e32 v67, 0xbfb8aa3b, v67
	v_rcp_f32_e32 v74, v66
	v_add_f32_e32 v66, 1.0, v71
	v_add_f32_e32 v71, v72, v124
	v_max_f32_e32 v71, 0xc1f00000, v71
	v_exp_f32_e32 v67, v67
	v_mul_f32_e32 v71, 0xbfb8aa3b, v71
	v_exp_f32_e32 v71, v71
	v_add_f32_e32 v68, v68, v128
	v_add_f32_e32 v67, 1.0, v67
	v_add_f32_e32 v70, v70, v122
	v_max_f32_e32 v68, 0xc1f00000, v68
	v_rcp_f32_e32 v72, v67
	v_add_f32_e32 v67, 1.0, v71
	v_add_f32_e32 v71, v73, v125
	v_add_f32_e32 v69, v69, v129
	v_max_f32_e32 v70, 0xc1f00000, v70
	v_mul_f32_e32 v68, 0xbfb8aa3b, v68
	v_max_f32_e32 v71, 0xc1f00000, v71
	v_max_f32_e32 v69, 0xc1f00000, v69
	v_mul_f32_e32 v70, 0xbfb8aa3b, v70
	v_exp_f32_e32 v68, v68
	v_mul_f32_e32 v71, 0xbfb8aa3b, v71
	v_mul_f32_e32 v69, 0xbfb8aa3b, v69
	v_exp_f32_e32 v70, v70
	v_exp_f32_e32 v71, v71
	v_exp_f32_e32 v69, v69
	v_add_f32_e32 v58, v58, v134
	v_add_f32_e32 v68, 1.0, v68
	v_max_f32_e32 v58, 0xc1f00000, v58
	v_add_f32_e32 v63, v63, v131
	v_add_f32_e32 v70, 1.0, v70
	v_rcp_f32_e32 v73, v68
	v_add_f32_e32 v68, 1.0, v71
	v_add_f32_e32 v69, 1.0, v69
	v_mul_f32_e32 v58, 0xbfb8aa3b, v58
	v_max_f32_e32 v63, 0xc1f00000, v63
	v_rcp_f32_e32 v70, v70
	v_rcp_f32_e32 v66, v66
	v_rcp_f32_e32 v67, v67
	v_rcp_f32_e32 v68, v68
	v_rcp_f32_e32 v69, v69
	v_exp_f32_e32 v58, v58
	v_mul_f32_e32 v63, 0xbfb8aa3b, v63
	v_exp_f32_e32 v63, v63
	v_cvt_pk_bf16_f32 v66, v70, v66
	v_cvt_pk_bf16_f32 v67, v67, v68
	v_cvt_pk_bf16_f32 v68, v74, v72
	v_cvt_pk_bf16_f32 v69, v73, v69
	v_add_f32_e32 v58, 1.0, v58
	v_add_f32_e32 v59, v59, v135
	global_store_dwordx4 v[82:83], v[66:69], off offset:256 sc1
	v_max_f32_e32 v59, 0xc1f00000, v59
	v_mul_f32_e32 v59, 0xbfb8aa3b, v59
	v_rcp_f32_e32 v68, v58
	v_add_f32_e32 v58, 1.0, v63
	v_add_f32_e32 v63, v64, v132
	v_max_f32_e32 v63, 0xc1f00000, v63
	v_exp_f32_e32 v59, v59
	v_mul_f32_e32 v63, 0xbfb8aa3b, v63
	v_exp_f32_e32 v63, v63
	v_add_f32_e32 v60, v60, v136
	v_add_f32_e32 v59, 1.0, v59
	v_add_f32_e32 v62, v62, v130
	v_max_f32_e32 v60, 0xc1f00000, v60
	v_rcp_f32_e32 v64, v59
	v_add_f32_e32 v59, 1.0, v63
	v_add_f32_e32 v63, v65, v133
	v_add_f32_e32 v61, v61, v137
	v_max_f32_e32 v62, 0xc1f00000, v62
	v_mul_f32_e32 v60, 0xbfb8aa3b, v60
	v_max_f32_e32 v63, 0xc1f00000, v63
	v_max_f32_e32 v61, 0xc1f00000, v61
	v_mul_f32_e32 v62, 0xbfb8aa3b, v62
	v_exp_f32_e32 v60, v60
	v_mul_f32_e32 v63, 0xbfb8aa3b, v63
	v_mul_f32_e32 v61, 0xbfb8aa3b, v61
	v_exp_f32_e32 v62, v62
	v_exp_f32_e32 v63, v63
	v_exp_f32_e32 v61, v61
	v_add_f32_e32 v50, v50, v126
	v_add_f32_e32 v60, 1.0, v60
	v_max_f32_e32 v50, 0xc1f00000, v50
	v_add_f32_e32 v55, v55, v123
	v_add_f32_e32 v62, 1.0, v62
	v_rcp_f32_e32 v65, v60
	v_add_f32_e32 v60, 1.0, v63
	v_add_f32_e32 v61, 1.0, v61
	v_mul_f32_e32 v50, 0xbfb8aa3b, v50
	v_max_f32_e32 v55, 0xc1f00000, v55
	v_rcp_f32_e32 v62, v62
	v_rcp_f32_e32 v58, v58
	v_rcp_f32_e32 v59, v59
	v_rcp_f32_e32 v60, v60
	v_rcp_f32_e32 v61, v61
	v_exp_f32_e32 v50, v50
	v_mul_f32_e32 v55, 0xbfb8aa3b, v55
	v_exp_f32_e32 v55, v55
	v_mad_i64_i32 v[66:67], s[0:1], v165, s87, v[156:157]
	v_cvt_pk_bf16_f32 v58, v62, v58
	v_cvt_pk_bf16_f32 v59, v59, v60
	v_cvt_pk_bf16_f32 v60, v68, v64
	v_cvt_pk_bf16_f32 v61, v65, v61
	v_add_f32_e32 v50, 1.0, v50
	v_add_f32_e32 v51, v51, v127
	global_store_dwordx4 v[66:67], v[58:61], off sc1
	v_max_f32_e32 v51, 0xc1f00000, v51
	v_mul_f32_e32 v51, 0xbfb8aa3b, v51
	v_rcp_f32_e32 v58, v50
	v_add_f32_e32 v50, 1.0, v55
	v_add_f32_e32 v55, v56, v124
	v_max_f32_e32 v55, 0xc1f00000, v55
	v_exp_f32_e32 v51, v51
	v_mul_f32_e32 v55, 0xbfb8aa3b, v55
	v_exp_f32_e32 v55, v55
	v_add_f32_e32 v52, v52, v128
	v_add_f32_e32 v51, 1.0, v51
	v_add_f32_e32 v54, v54, v122
	v_max_f32_e32 v52, 0xc1f00000, v52
	v_rcp_f32_e32 v56, v51
	v_add_f32_e32 v51, 1.0, v55
	v_add_f32_e32 v55, v57, v125
	v_add_f32_e32 v53, v53, v129
	v_max_f32_e32 v54, 0xc1f00000, v54
	v_mul_f32_e32 v52, 0xbfb8aa3b, v52
	v_max_f32_e32 v55, 0xc1f00000, v55
	v_max_f32_e32 v53, 0xc1f00000, v53
	v_mul_f32_e32 v54, 0xbfb8aa3b, v54
	v_exp_f32_e32 v52, v52
	v_mul_f32_e32 v55, 0xbfb8aa3b, v55
	v_mul_f32_e32 v53, 0xbfb8aa3b, v53
	v_exp_f32_e32 v54, v54
	v_exp_f32_e32 v55, v55
	v_exp_f32_e32 v53, v53
	v_add_f32_e32 v42, v42, v134
	v_add_f32_e32 v52, 1.0, v52
	v_max_f32_e32 v42, 0xc1f00000, v42
	v_add_f32_e32 v47, v47, v131
	v_add_f32_e32 v54, 1.0, v54
	v_rcp_f32_e32 v57, v52
	v_add_f32_e32 v52, 1.0, v55
	v_add_f32_e32 v53, 1.0, v53
	v_mul_f32_e32 v42, 0xbfb8aa3b, v42
	v_max_f32_e32 v47, 0xc1f00000, v47
	v_rcp_f32_e32 v54, v54
	v_rcp_f32_e32 v50, v50
	v_rcp_f32_e32 v51, v51
	v_rcp_f32_e32 v52, v52
	v_rcp_f32_e32 v53, v53
	v_exp_f32_e32 v42, v42
	v_mul_f32_e32 v47, 0xbfb8aa3b, v47
	v_exp_f32_e32 v47, v47
	v_cvt_pk_bf16_f32 v50, v54, v50
	v_cvt_pk_bf16_f32 v51, v51, v52
	v_cvt_pk_bf16_f32 v52, v58, v56
	v_cvt_pk_bf16_f32 v53, v57, v53
	v_add_f32_e32 v42, 1.0, v42
	v_add_f32_e32 v43, v43, v135
	global_store_dwordx4 v[66:67], v[50:53], off offset:256 sc1
	v_max_f32_e32 v43, 0xc1f00000, v43
	v_mul_f32_e32 v43, 0xbfb8aa3b, v43
	v_rcp_f32_e32 v52, v42
	v_add_f32_e32 v42, 1.0, v47
	v_add_f32_e32 v47, v48, v132
	v_max_f32_e32 v47, 0xc1f00000, v47
	v_exp_f32_e32 v43, v43
	v_mul_f32_e32 v47, 0xbfb8aa3b, v47
	v_exp_f32_e32 v47, v47
	v_add_f32_e32 v44, v44, v136
	v_add_f32_e32 v43, 1.0, v43
	v_add_f32_e32 v46, v46, v130
	v_max_f32_e32 v44, 0xc1f00000, v44
	v_rcp_f32_e32 v48, v43
	v_add_f32_e32 v43, 1.0, v47
	v_add_f32_e32 v47, v49, v133
	v_add_f32_e32 v45, v45, v137
	v_max_f32_e32 v46, 0xc1f00000, v46
	v_mul_f32_e32 v44, 0xbfb8aa3b, v44
	v_max_f32_e32 v47, 0xc1f00000, v47
	v_max_f32_e32 v45, 0xc1f00000, v45
	v_mul_f32_e32 v46, 0xbfb8aa3b, v46
	v_exp_f32_e32 v44, v44
	v_mul_f32_e32 v47, 0xbfb8aa3b, v47
	v_mul_f32_e32 v45, 0xbfb8aa3b, v45
	v_exp_f32_e32 v46, v46
	v_exp_f32_e32 v47, v47
	v_exp_f32_e32 v45, v45
	v_add_f32_e32 v34, v34, v126
	v_add_f32_e32 v44, 1.0, v44
	v_max_f32_e32 v34, 0xc1f00000, v34
	v_add_f32_e32 v39, v39, v123
	v_add_f32_e32 v46, 1.0, v46
	v_rcp_f32_e32 v49, v44
	v_add_f32_e32 v44, 1.0, v47
	v_add_f32_e32 v45, 1.0, v45
	v_mul_f32_e32 v34, 0xbfb8aa3b, v34
	v_max_f32_e32 v39, 0xc1f00000, v39
	v_rcp_f32_e32 v46, v46
	v_rcp_f32_e32 v42, v42
	v_rcp_f32_e32 v43, v43
	v_rcp_f32_e32 v44, v44
	v_rcp_f32_e32 v45, v45
	v_exp_f32_e32 v34, v34
	v_mul_f32_e32 v39, 0xbfb8aa3b, v39
	v_exp_f32_e32 v39, v39
	v_mad_i64_i32 v[50:51], s[0:1], v164, s87, v[156:157]
	v_cvt_pk_bf16_f32 v42, v46, v42
	v_cvt_pk_bf16_f32 v43, v43, v44
	v_cvt_pk_bf16_f32 v44, v52, v48
	v_cvt_pk_bf16_f32 v45, v49, v45
	v_add_f32_e32 v34, 1.0, v34
	v_add_f32_e32 v35, v35, v127
	global_store_dwordx4 v[50:51], v[42:45], off sc1
	v_max_f32_e32 v35, 0xc1f00000, v35
	v_mul_f32_e32 v35, 0xbfb8aa3b, v35
	v_rcp_f32_e32 v42, v34
	v_add_f32_e32 v34, 1.0, v39
	v_add_f32_e32 v39, v40, v124
	v_max_f32_e32 v39, 0xc1f00000, v39
	v_exp_f32_e32 v35, v35
	v_mul_f32_e32 v39, 0xbfb8aa3b, v39
	v_exp_f32_e32 v39, v39
	v_add_f32_e32 v36, v36, v128
	v_add_f32_e32 v35, 1.0, v35
	v_add_f32_e32 v38, v38, v122
	v_max_f32_e32 v36, 0xc1f00000, v36
	v_rcp_f32_e32 v40, v35
	v_add_f32_e32 v35, 1.0, v39
	v_add_f32_e32 v39, v41, v125
	v_add_f32_e32 v37, v37, v129
	v_max_f32_e32 v38, 0xc1f00000, v38
	v_mul_f32_e32 v36, 0xbfb8aa3b, v36
	v_max_f32_e32 v39, 0xc1f00000, v39
	v_max_f32_e32 v37, 0xc1f00000, v37
	v_mul_f32_e32 v38, 0xbfb8aa3b, v38
	v_exp_f32_e32 v36, v36
	v_mul_f32_e32 v39, 0xbfb8aa3b, v39
	v_mul_f32_e32 v37, 0xbfb8aa3b, v37
	v_exp_f32_e32 v38, v38
	v_exp_f32_e32 v39, v39
	v_exp_f32_e32 v37, v37
	v_add_f32_e32 v26, v26, v134
	v_add_f32_e32 v36, 1.0, v36
	v_max_f32_e32 v26, 0xc1f00000, v26
	v_add_f32_e32 v31, v31, v131
	v_add_f32_e32 v38, 1.0, v38
	v_rcp_f32_e32 v41, v36
	v_add_f32_e32 v36, 1.0, v39
	v_add_f32_e32 v37, 1.0, v37
	v_mul_f32_e32 v26, 0xbfb8aa3b, v26
	v_max_f32_e32 v31, 0xc1f00000, v31
	v_rcp_f32_e32 v38, v38
	v_rcp_f32_e32 v34, v34
	v_rcp_f32_e32 v35, v35
	v_rcp_f32_e32 v36, v36
	v_rcp_f32_e32 v37, v37
	v_exp_f32_e32 v26, v26
	v_mul_f32_e32 v31, 0xbfb8aa3b, v31
	v_exp_f32_e32 v31, v31
	v_cvt_pk_bf16_f32 v34, v38, v34
	v_cvt_pk_bf16_f32 v35, v35, v36
	v_cvt_pk_bf16_f32 v36, v42, v40
	v_cvt_pk_bf16_f32 v37, v41, v37
	v_add_f32_e32 v26, 1.0, v26
	v_add_f32_e32 v27, v27, v135
	global_store_dwordx4 v[50:51], v[34:37], off offset:256 sc1
	v_max_f32_e32 v27, 0xc1f00000, v27
	v_mul_f32_e32 v27, 0xbfb8aa3b, v27
	v_rcp_f32_e32 v36, v26
	v_add_f32_e32 v26, 1.0, v31
	v_add_f32_e32 v31, v32, v132
	v_max_f32_e32 v31, 0xc1f00000, v31
	v_exp_f32_e32 v27, v27
	v_mul_f32_e32 v31, 0xbfb8aa3b, v31
	v_exp_f32_e32 v31, v31
	v_add_f32_e32 v28, v28, v136
	v_add_f32_e32 v27, 1.0, v27
	v_add_f32_e32 v30, v30, v130
	v_max_f32_e32 v28, 0xc1f00000, v28
	v_rcp_f32_e32 v32, v27
	v_add_f32_e32 v27, 1.0, v31
	v_add_f32_e32 v31, v33, v133
	v_add_f32_e32 v29, v29, v137
	v_max_f32_e32 v30, 0xc1f00000, v30
	v_mul_f32_e32 v28, 0xbfb8aa3b, v28
	v_max_f32_e32 v31, 0xc1f00000, v31
	v_max_f32_e32 v29, 0xc1f00000, v29
	v_mul_f32_e32 v30, 0xbfb8aa3b, v30
	v_exp_f32_e32 v28, v28
	v_mul_f32_e32 v31, 0xbfb8aa3b, v31
	v_mul_f32_e32 v29, 0xbfb8aa3b, v29
	v_exp_f32_e32 v30, v30
	v_exp_f32_e32 v31, v31
	v_exp_f32_e32 v29, v29
	v_add_f32_e32 v18, v18, v126
	v_add_f32_e32 v28, 1.0, v28
	v_max_f32_e32 v18, 0xc1f00000, v18
	v_add_f32_e32 v23, v23, v123
	v_add_f32_e32 v30, 1.0, v30
	v_rcp_f32_e32 v33, v28
	v_add_f32_e32 v28, 1.0, v31
	v_add_f32_e32 v29, 1.0, v29
	v_mul_f32_e32 v18, 0xbfb8aa3b, v18
	v_max_f32_e32 v23, 0xc1f00000, v23
	v_rcp_f32_e32 v30, v30
	v_rcp_f32_e32 v26, v26
	v_rcp_f32_e32 v27, v27
	v_rcp_f32_e32 v28, v28
	v_rcp_f32_e32 v29, v29
	v_exp_f32_e32 v18, v18
	v_mul_f32_e32 v23, 0xbfb8aa3b, v23
	v_exp_f32_e32 v23, v23
	v_mad_i64_i32 v[34:35], s[0:1], v163, s87, v[156:157]
	v_cvt_pk_bf16_f32 v26, v30, v26
	v_cvt_pk_bf16_f32 v27, v27, v28
	v_cvt_pk_bf16_f32 v28, v36, v32
	v_cvt_pk_bf16_f32 v29, v33, v29
	v_add_f32_e32 v18, 1.0, v18
	v_add_f32_e32 v19, v19, v127
	global_store_dwordx4 v[34:35], v[26:29], off sc1
	v_max_f32_e32 v19, 0xc1f00000, v19
	v_mul_f32_e32 v19, 0xbfb8aa3b, v19
	v_rcp_f32_e32 v26, v18
	v_add_f32_e32 v18, 1.0, v23
	v_add_f32_e32 v23, v24, v124
	v_max_f32_e32 v23, 0xc1f00000, v23
	v_exp_f32_e32 v19, v19
	v_mul_f32_e32 v23, 0xbfb8aa3b, v23
	v_exp_f32_e32 v23, v23
	v_add_f32_e32 v20, v20, v128
	v_add_f32_e32 v19, 1.0, v19
	v_add_f32_e32 v22, v22, v122
	v_max_f32_e32 v20, 0xc1f00000, v20
	v_rcp_f32_e32 v24, v19
	v_add_f32_e32 v19, 1.0, v23
	v_add_f32_e32 v23, v25, v125
	v_add_f32_e32 v21, v21, v129
	v_max_f32_e32 v22, 0xc1f00000, v22
	v_mul_f32_e32 v20, 0xbfb8aa3b, v20
	v_max_f32_e32 v23, 0xc1f00000, v23
	v_max_f32_e32 v21, 0xc1f00000, v21
	v_mul_f32_e32 v22, 0xbfb8aa3b, v22
	v_exp_f32_e32 v20, v20
	v_mul_f32_e32 v23, 0xbfb8aa3b, v23
	v_mul_f32_e32 v21, 0xbfb8aa3b, v21
	v_exp_f32_e32 v22, v22
	v_exp_f32_e32 v23, v23
	v_exp_f32_e32 v21, v21
	v_add_f32_e32 v10, v10, v134
	v_add_f32_e32 v20, 1.0, v20
	v_max_f32_e32 v10, 0xc1f00000, v10
	v_add_f32_e32 v15, v15, v131
	v_add_f32_e32 v22, 1.0, v22
	v_rcp_f32_e32 v25, v20
	v_add_f32_e32 v20, 1.0, v23
	v_add_f32_e32 v21, 1.0, v21
	v_mul_f32_e32 v10, 0xbfb8aa3b, v10
	v_max_f32_e32 v15, 0xc1f00000, v15
	v_rcp_f32_e32 v22, v22
	v_rcp_f32_e32 v18, v18
	v_rcp_f32_e32 v19, v19
	v_rcp_f32_e32 v20, v20
	v_rcp_f32_e32 v21, v21
	v_exp_f32_e32 v10, v10
	v_mul_f32_e32 v15, 0xbfb8aa3b, v15
	v_exp_f32_e32 v15, v15
	v_cvt_pk_bf16_f32 v18, v22, v18
	v_cvt_pk_bf16_f32 v19, v19, v20
	v_cvt_pk_bf16_f32 v20, v26, v24
	v_cvt_pk_bf16_f32 v21, v25, v21
	v_add_f32_e32 v10, 1.0, v10
	v_add_f32_e32 v11, v11, v135
	global_store_dwordx4 v[34:35], v[18:21], off offset:256 sc1
	v_max_f32_e32 v11, 0xc1f00000, v11
	v_mul_f32_e32 v11, 0xbfb8aa3b, v11
	v_rcp_f32_e32 v18, v10
	v_add_f32_e32 v10, 1.0, v15
	v_add_f32_e32 v15, v16, v132
	v_max_f32_e32 v15, 0xc1f00000, v15
	v_exp_f32_e32 v11, v11
	v_mul_f32_e32 v15, 0xbfb8aa3b, v15
	v_exp_f32_e32 v15, v15
	v_add_f32_e32 v142, v142, v130
	v_add_f32_e32 v141, v141, v137
	v_add_f32_e32 v11, 1.0, v11
	v_add_f32_e32 v12, v12, v136
	v_max_f32_e32 v142, 0xc1f00000, v142
	v_max_f32_e32 v141, 0xc1f00000, v141
	v_add_f32_e32 v14, v14, v130
	v_max_f32_e32 v12, 0xc1f00000, v12
	v_rcp_f32_e32 v16, v11
	v_add_f32_e32 v11, 1.0, v15
	v_add_f32_e32 v15, v17, v133
	v_add_f32_e32 v13, v13, v137
	v_add_f32_e32 v6, v6, v122
	v_add_f32_e32 v2, v2, v126
	v_add_f32_e32 v7, v7, v123
	v_add_f32_e32 v3, v3, v127
	v_add_f32_e32 v8, v8, v124
	v_add_f32_e32 v9, v9, v125
	v_mul_f32_e32 v142, 0xbfb8aa3b, v142
	v_mul_f32_e32 v141, 0xbfb8aa3b, v141
	v_max_f32_e32 v14, 0xc1f00000, v14
	v_mul_f32_e32 v12, 0xbfb8aa3b, v12
	v_max_f32_e32 v15, 0xc1f00000, v15
	v_max_f32_e32 v13, 0xc1f00000, v13
	v_max_f32_e32 v6, 0xc1f00000, v6
	v_max_f32_e32 v2, 0xc1f00000, v2
	v_max_f32_e32 v7, 0xc1f00000, v7
	v_max_f32_e32 v3, 0xc1f00000, v3
	v_max_f32_e32 v8, 0xc1f00000, v8
	v_add_f32_e32 v4, v4, v128
	v_max_f32_e32 v9, 0xc1f00000, v9
	v_add_f32_e32 v5, v5, v129
	v_exp_f32_e32 v142, v142
	v_exp_f32_e32 v141, v141
	v_mul_f32_e32 v14, 0xbfb8aa3b, v14
	v_exp_f32_e32 v12, v12
	v_mul_f32_e32 v15, 0xbfb8aa3b, v15
	v_mul_f32_e32 v13, 0xbfb8aa3b, v13
	v_mul_f32_e32 v6, 0xbfb8aa3b, v6
	v_mul_f32_e32 v2, 0xbfb8aa3b, v2
	v_mul_f32_e32 v7, 0xbfb8aa3b, v7
	v_mul_f32_e32 v3, 0xbfb8aa3b, v3
	v_mul_f32_e32 v8, 0xbfb8aa3b, v8
	v_max_f32_e32 v4, 0xc1f00000, v4
	v_mul_f32_e32 v9, 0xbfb8aa3b, v9
	v_max_f32_e32 v5, 0xc1f00000, v5
	v_exp_f32_e32 v14, v14
	v_exp_f32_e32 v15, v15
	v_exp_f32_e32 v13, v13
	v_exp_f32_e32 v6, v6
	v_exp_f32_e32 v2, v2
	v_exp_f32_e32 v7, v7
	v_exp_f32_e32 v3, v3
	v_exp_f32_e32 v8, v8
	v_mul_f32_e32 v4, 0xbfb8aa3b, v4
	v_exp_f32_e32 v9, v9
	v_mul_f32_e32 v5, 0xbfb8aa3b, v5
	v_exp_f32_e32 v4, v4
	v_exp_f32_e32 v5, v5
	v_add_f32_e32 v142, 1.0, v142
	v_add_f32_e32 v141, 1.0, v141
	v_add_f32_e32 v12, 1.0, v12
	v_rcp_f32_e32 v142, v142
	v_rcp_f32_e32 v141, v141
	v_add_f32_e32 v14, 1.0, v14
	v_rcp_f32_e32 v17, v12
	v_add_f32_e32 v12, 1.0, v15
	v_add_f32_e32 v13, 1.0, v13
	v_add_f32_e32 v6, 1.0, v6
	v_add_f32_e32 v2, 1.0, v2
	v_add_f32_e32 v7, 1.0, v7
	v_add_f32_e32 v3, 1.0, v3
	v_add_f32_e32 v8, 1.0, v8
	v_add_f32_e32 v9, 1.0, v9
	v_rcp_f32_e32 v14, v14
	v_rcp_f32_e32 v10, v10
	v_rcp_f32_e32 v11, v11
	v_rcp_f32_e32 v12, v12
	v_rcp_f32_e32 v13, v13
	v_rcp_f32_e32 v6, v6
	v_rcp_f32_e32 v2, v2
	v_rcp_f32_e32 v7, v7
	v_rcp_f32_e32 v3, v3
	v_rcp_f32_e32 v8, v8
	v_add_f32_e32 v4, 1.0, v4
	v_rcp_f32_e32 v9, v9
	v_add_f32_e32 v5, 1.0, v5
	v_rcp_f32_e32 v4, v4
	v_rcp_f32_e32 v5, v5
	v_cvt_pk_bf16_f32 v138, v142, v138
	v_cvt_pk_bf16_f32 v139, v139, v140
	v_cvt_pk_bf16_f32 v140, v169, v143
	v_cvt_pk_bf16_f32 v141, v144, v141
	global_store_dwordx4 v[158:159], v[138:141], off sc1
	v_mad_i64_i32 v[158:159], s[0:1], v162, s87, v[156:157]
	v_cvt_pk_bf16_f32 v10, v14, v10
	v_cvt_pk_bf16_f32 v11, v11, v12
	v_cvt_pk_bf16_f32 v12, v18, v16
	v_cvt_pk_bf16_f32 v13, v17, v13
	v_cvt_pk_bf16_f32 v122, v6, v7
	v_cvt_pk_bf16_f32 v123, v8, v9
	v_cvt_pk_bf16_f32 v124, v2, v3
	global_store_dwordx4 v[158:159], v[10:13], off sc1
.LBB0_131:
	v_cvt_pk_bf16_f32 v125, v4, v5
	s_andn2_b64 vcc, exec, s[22:23]
	s_mov_b64 s[0:1], -1
	global_store_dwordx4 v[158:159], v[122:125], off offset:256 sc1
	s_cbranch_vccnz .LBB0_109
	s_andn2_b64 vcc, exec, s[12:13]
	s_cbranch_vccnz .LBB0_108
	s_barrier
	s_branch .LBB0_108
